# attention: Q fragments held in registers (read from LDS once per unit), K fragments through 4 rotating buffers, running-max reference applied with v_add after QK instead of MFMA C operand; plus early
# baseline (speedup 1.0000x reference)
.LBB0_297:
	s_and_b32 s15, s19, -2
	s_add_i32 s30, s14, s15
	s_add_i32 s90, s0, s15
	s_ashr_i32 s31, s30, 31
	s_and_b32 s15, s19, 2
	s_lshl_b64 s[26:27], s[90:91], 9
	s_lshl_b64 s[30:31], s[30:31], 21
	s_or_b32 s44, s0, s15
	s_bitcmp0_b32 s19, 0
	s_cselect_b32 s78, s86, s2
	s_lshl_b32 s15, s78, 7
	v_readlane_b32 s42, v251, 60
	s_or_b32 s15, s15, s42
	s_lshl_b32 s45, s78, 2
	s_or_b32 s80, s6, s15
	s_mov_b32 s81, s7
	s_add_i32 s77, s45, 4
	s_lshl_b64 s[42:43], s[80:81], 12
	s_add_u32 s15, s92, s42
	s_addc_u32 s42, s74, s43
	s_lshl_b32 s76, s44, 8
	s_lshl_b32 s90, s44, 9
	s_add_u32 s15, s15, s90
	v_mbcnt_lo_u32_b32 v74, -1, 0
	v_mbcnt_hi_u32_b32 v74, -1, v74
	s_addc_u32 s43, s42, 0
	v_add_u32_e32 v3, 64, v74
	v_lshlrev_b32_e32 v75, 4, v74
	s_add_u32 s42, s15, s18
	v_ashrrev_i32_e32 v56, 4, v74
	v_ashrrev_i32_e32 v58, 4, v3
	v_add_u32_e32 v3, 0x80, v74
	v_and_b32_e32 v0, 0xf0, v75
	s_addc_u32 s43, s43, 0
	v_ashrrev_i32_e32 v57, 31, v56
	v_ashrrev_i32_e32 v59, 31, v58
	v_ashrrev_i32_e32 v60, 4, v3
	v_add_u32_e32 v3, 0xc0, v74
	v_lshl_add_u64 v[30:31], s[42:43], 0, v[0:1]
	v_lshlrev_b64 v[6:7], 12, v[56:57]
	v_lshlrev_b64 v[8:9], 12, v[58:59]
	v_ashrrev_i32_e32 v62, 4, v3
	v_add_u32_e32 v3, 0x100, v74
	v_lshl_add_u64 v[6:7], v[30:31], 0, v[6:7]
	v_lshl_add_u64 v[10:11], v[30:31], 0, v[8:9]
	v_ashrrev_i32_e32 v61, 31, v60
	v_ashrrev_i32_e32 v63, 31, v62
	v_ashrrev_i32_e32 v64, 4, v3
	v_add_u32_e32 v3, 0x140, v74
	global_load_dwordx4 v[6:9], v[6:7], off
	s_nop 0
	global_load_dwordx4 v[10:13], v[10:11], off
	v_lshlrev_b64 v[14:15], 12, v[60:61]
	v_lshlrev_b64 v[16:17], 12, v[62:63]
	v_ashrrev_i32_e32 v66, 4, v3
	v_add_u32_e32 v3, 0x180, v74
	v_lshl_add_u64 v[14:15], v[30:31], 0, v[14:15]
	v_lshl_add_u64 v[18:19], v[30:31], 0, v[16:17]
	v_ashrrev_i32_e32 v65, 31, v64
	v_ashrrev_i32_e32 v67, 31, v66
	v_ashrrev_i32_e32 v68, 4, v3
	v_add_u32_e32 v3, 0x1c0, v74
	global_load_dwordx4 v[14:17], v[14:15], off
	s_nop 0
	global_load_dwordx4 v[18:21], v[18:19], off
	v_lshlrev_b64 v[22:23], 12, v[64:65]
	v_lshlrev_b64 v[24:25], 12, v[66:67]
	v_ashrrev_i32_e32 v70, 4, v3
	v_lshl_add_u64 v[22:23], v[30:31], 0, v[22:23]
	v_lshl_add_u64 v[26:27], v[30:31], 0, v[24:25]
	v_ashrrev_i32_e32 v69, 31, v68
	v_ashrrev_i32_e32 v71, 31, v70
	global_load_dwordx4 v[22:25], v[22:23], off
	s_nop 0
	global_load_dwordx4 v[26:29], v[26:27], off
	v_lshlrev_b64 v[32:33], 12, v[68:69]
	v_lshlrev_b64 v[34:35], 12, v[70:71]
	v_lshl_add_u64 v[32:33], v[30:31], 0, v[32:33]
	v_lshl_add_u64 v[34:35], v[30:31], 0, v[34:35]
	global_load_dwordx4 v[30:33], v[32:33], off
	s_nop 0
	global_load_dwordx4 v[34:37], v[34:35], off
	v_add_u32_e32 v2, s3, v74
	v_ashrrev_i32_e32 v4, 4, v2
	v_ashrrev_i32_e32 v5, 31, v4
	s_or_b32 s42, s44, s87
	v_lshl_add_u64 v[38:39], s[6:7], 0, v[4:5]
	s_ashr_i32 s43, s42, 31
	v_ashrrev_i32_e32 v54, 2, v2
	s_or_b32 s15, s45, s79
	v_lshlrev_b64 v[38:39], 12, v[38:39]
	s_lshl_b64 s[42:43], s[42:43], 21
	v_lshl_add_u64 v[38:39], s[36:37], 0, v[38:39]
	v_ashrrev_i32_e32 v55, 31, v54
	s_add_u32 s42, s38, s42
	v_lshlrev_b64 v[72:73], 6, v[54:55]
	v_lshl_add_u64 v[38:39], v[38:39], 0, s[90:91]
	s_addc_u32 s43, s39, s43
	v_and_b32_e32 v2, 48, v75
	v_lshl_add_u64 v[42:43], v[38:39], 0, v[0:1]
	v_lshl_add_u64 v[38:39], s[42:43], 0, v[72:73]
	v_mov_b32_e32 v3, v1
	v_lshl_add_u64 v[50:51], v[38:39], 0, v[2:3]
	global_load_dwordx4 v[38:41], v[42:43], off
	s_nop 0
	global_load_dwordx4 v[42:45], v[42:43], off offset:256
	s_nop 0
	global_load_dwordx4 v[46:49], v[50:51], off
	v_add_co_u32_e32 v50, vcc, s9, v50
	s_movk_i32 s42, 0x50
	s_nop 0
	v_addc_co_u32_e32 v51, vcc, 0, v51, vcc
	global_load_dwordx4 v[50:53], v[50:51], off
	v_mul_lo_u32 v55, v54, s42
	v_lshlrev_b32_e32 v54, 3, v74
	v_and_b32_e32 v54, 8, v54
	v_readlane_b32 s42, v251, 61
	v_and_or_b32 v59, v75, 32, v54
	v_and_b32_e32 v3, 31, v74
	v_add_u32_e32 v54, s42, v0
	v_mad_u64_u32 v[56:57], s[42:43], v56, s33, v[54:55]
	s_lshl_b32 s78, s78, 16
	s_or_b32 s90, s93, s78
	s_add_u32 s96, s41, s78
	v_mov_b32_e32 v232, 0
	v_mov_b32_e32 v235, 0
	s_mov_b32 s97, 0
	s_waitcnt vmcnt(11)
	ds_write_b128 v56, v[6:9]
	v_mad_u64_u32 v[6:7], s[42:43], v58, s33, v[54:55]
	s_waitcnt vmcnt(10)
	ds_write_b128 v6, v[10:13]
	v_mad_u64_u32 v[6:7], s[42:43], v60, s33, v[54:55]
	v_ashrrev_i32_e32 v8, 5, v74
	v_mov_b32_e32 v9, v1
	v_mov_b32_e32 v10, v1
	v_mov_b32_e32 v11, v1
	v_mov_b32_e32 v12, v1
	s_waitcnt vmcnt(9)
	ds_write_b128 v6, v[14:17]
	v_mad_u64_u32 v[6:7], s[42:43], v62, s33, v[54:55]
	s_waitcnt vmcnt(8)
	ds_write_b128 v6, v[18:21]
	v_mad_u64_u32 v[6:7], s[42:43], v64, s33, v[54:55]
	v_lshlrev_b32_e32 v16, 4, v8
	v_mad_u32_u24 v206, v3, s33, v16
	s_waitcnt vmcnt(7)
	ds_write_b128 v6, v[22:25]
	v_mad_u64_u32 v[6:7], s[42:43], v66, s33, v[54:55]
	s_waitcnt vmcnt(6)
	ds_write_b128 v6, v[26:29]
	v_mad_u64_u32 v[6:7], s[42:43], v68, s33, v[54:55]
	s_waitcnt vmcnt(5)
	ds_write_b128 v6, v[30:33]
	v_mad_u64_u32 v[6:7], s[42:43], v70, s33, v[54:55]
	s_waitcnt vmcnt(4)
	ds_write_b128 v6, v[34:37]
	v_mad_u64_u32 v[6:7], s[42:43], v4, s33, v[0:1]
	v_add_u32_e32 v207, 0, v6
	v_add3_u32 v6, v55, v59, 0
	v_add_u32_e32 v208, 0x4000, v6
	v_add_u32_e32 v209, 0x6800, v6
	v_add_u32_e32 v210, 0xd800, v6
	v_mul_u32_u24_e32 v6, 0x50, v3
	v_add_u32_e32 v7, s8, v206
	v_add3_u32 v218, 0, v6, v16
	v_lshlrev_b32_e32 v6, 2, v8
	v_add_u32_e32 v211, 0x12800, v7
	v_add_u32_e32 v219, 0x12820, v7
	v_add_u32_e32 v220, 0x12840, v7
	v_add_u32_e32 v221, 0x12860, v7
	v_add_u32_e32 v222, 0x12880, v7
	v_add_u32_e32 v223, 0x128a0, v7
	v_add_u32_e32 v224, 0x128c0, v7
	v_add_u32_e32 v225, 0x128e0, v7
	v_or_b32_e32 v7, 2, v6
	v_cmp_gt_i32_e64 s[46:47], v7, v3
	v_or_b32_e32 v7, 3, v6
	v_cmp_gt_i32_e64 s[48:49], v7, v3
	v_add_u32_e32 v7, 8, v6
	v_cmp_gt_i32_e64 s[50:51], v7, v3
	v_cmp_lt_i32_e64 s[52:53], v7, v3
	v_add_u32_e32 v7, 10, v6
	v_cmp_gt_i32_e64 s[54:55], v7, v3
	v_add_u32_e32 v7, 11, v6
	v_cmp_gt_i32_e64 s[56:57], v7, v3
	v_add_u32_e32 v7, 16, v6
	v_lshlrev_b64 v[4:5], 12, v[4:5]
	v_cmp_gt_i32_e64 s[58:59], v7, v3
	v_cmp_lt_i32_e64 s[60:61], v7, v3
	v_add_u32_e32 v7, 18, v6
	v_lshl_add_u64 v[4:5], v[4:5], 0, s[26:27]
	v_cmp_gt_i32_e64 s[62:63], v7, v3
	v_add_u32_e32 v7, 19, v6
	v_or_b32_e32 v4, v4, v0
	v_mov_b32_e32 v8, s40
	v_cmp_gt_i32_e64 s[64:65], v7, v3
	v_add_u32_e32 v7, 24, v6
	v_lshl_add_u64 v[200:201], s[84:85], 0, v[4:5]
	v_lshl_add_u64 v[4:5], s[30:31], 0, v[72:73]
	v_mad_u32_u24 v17, v3, s33, v8
	v_cmp_gt_i32_e64 s[42:43], v6, v3
	v_cmp_lt_i32_e64 s[44:45], v6, v3
	v_cmp_gt_i32_e64 s[66:67], v7, v3
	v_cmp_lt_i32_e64 s[68:69], v7, v3
	v_add_u32_e32 v7, 26, v6
	v_add_u32_e32 v6, 27, v6
	v_or_b32_e32 v4, v4, v2
	v_mov_b32_e32 v14, v1
	v_mov_b32_e32 v15, v1
	s_waitcnt vmcnt(3)
	ds_write_b128 v207, v[38:41]
	s_waitcnt vmcnt(2)
	ds_write_b128 v207, v[42:45] offset:8704
	s_waitcnt vmcnt(1)
	ds_write2_b64 v208, v[46:47], v[48:49] offset0:128 offset1:130
	s_waitcnt vmcnt(0)
	ds_write2_b64 v209, v[50:51], v[52:53] offset0:128 offset1:130
	v_cmp_gt_i32_e64 s[70:71], v7, v3
	v_cmp_gt_i32_e64 s[72:73], v6, v3
	v_lshl_add_u64 v[202:203], s[38:39], 0, v[4:5]
	v_mov_b32_e32 v0, v1
	v_mov_b32_e32 v2, v1
	v_mov_b32_e32 v3, v1
	v_mov_b32_e32 v4, v1
	v_mov_b32_e32 v5, v1
	v_mov_b32_e32 v6, v1
	v_mov_b32_e32 v7, v1
	v_mov_b32_e32 v8, v1
	v_mov_b32_e32 v13, v1
	v_add_u32_e32 v233, v17, v16
	v_mov_b64_e32 v[30:31], v[14:15]
	v_mov_b64_e32 v[46:47], v[14:15]
	v_mov_b64_e32 v[62:63], v[14:15]
	v_mov_b64_e32 v[78:79], v[14:15]
	v_mov_b64_e32 v[94:95], v[14:15]
	v_mov_b64_e32 v[110:111], v[14:15]
	v_mov_b64_e32 v[126:127], v[14:15]
	v_mov_b64_e32 v[142:143], v[14:15]
	v_mov_b64_e32 v[158:159], v[14:15]
	v_add_u32_e32 v226, 0x10a00, v218
	v_add_u32_e32 v227, 0x10a20, v218
	v_add_u32_e32 v228, 0x11400, v218
	v_add_u32_e32 v229, 0x11420, v218
	v_add_u32_e32 v230, 0x11e00, v218
	v_add_u32_e32 v231, 0x11e20, v218
	s_mov_b64 s[26:27], 0
	v_add_u32_e32 v234, 0x2800, v210
	v_mov_b64_e32 v[28:29], v[12:13]
	v_mov_b64_e32 v[26:27], v[10:11]
	v_mov_b64_e32 v[24:25], v[8:9]
	v_mov_b64_e32 v[22:23], v[6:7]
	v_mov_b64_e32 v[20:21], v[4:5]
	v_mov_b64_e32 v[18:19], v[2:3]
	v_mov_b64_e32 v[16:17], v[0:1]
	v_mov_b64_e32 v[44:45], v[12:13]
	v_mov_b64_e32 v[42:43], v[10:11]
	v_mov_b64_e32 v[40:41], v[8:9]
	v_mov_b64_e32 v[38:39], v[6:7]
	v_mov_b64_e32 v[36:37], v[4:5]
	v_mov_b64_e32 v[34:35], v[2:3]
	v_mov_b64_e32 v[32:33], v[0:1]
	v_mov_b64_e32 v[60:61], v[12:13]
	v_mov_b64_e32 v[58:59], v[10:11]
	v_mov_b64_e32 v[56:57], v[8:9]
	v_mov_b64_e32 v[54:55], v[6:7]
	v_mov_b64_e32 v[52:53], v[4:5]
	v_mov_b64_e32 v[50:51], v[2:3]
	v_mov_b64_e32 v[48:49], v[0:1]
	v_mov_b64_e32 v[76:77], v[12:13]
	v_mov_b64_e32 v[74:75], v[10:11]
	v_mov_b64_e32 v[72:73], v[8:9]
	v_mov_b64_e32 v[70:71], v[6:7]
	v_mov_b64_e32 v[68:69], v[4:5]
	v_mov_b64_e32 v[66:67], v[2:3]
	v_mov_b64_e32 v[64:65], v[0:1]
	v_mov_b64_e32 v[92:93], v[12:13]
	v_mov_b64_e32 v[90:91], v[10:11]
	v_mov_b64_e32 v[88:89], v[8:9]
	v_mov_b64_e32 v[86:87], v[6:7]
	v_mov_b64_e32 v[84:85], v[4:5]
	v_mov_b64_e32 v[82:83], v[2:3]
	v_mov_b64_e32 v[80:81], v[0:1]
	v_mov_b64_e32 v[108:109], v[12:13]
	v_mov_b64_e32 v[106:107], v[10:11]
	v_mov_b64_e32 v[104:105], v[8:9]
	v_mov_b64_e32 v[102:103], v[6:7]
	v_mov_b64_e32 v[100:101], v[4:5]
	v_mov_b64_e32 v[98:99], v[2:3]
	v_mov_b64_e32 v[96:97], v[0:1]
	v_mov_b64_e32 v[124:125], v[12:13]
	v_mov_b64_e32 v[122:123], v[10:11]
	v_mov_b64_e32 v[120:121], v[8:9]
	v_mov_b64_e32 v[118:119], v[6:7]
	v_mov_b64_e32 v[116:117], v[4:5]
	v_mov_b64_e32 v[114:115], v[2:3]
	v_mov_b64_e32 v[112:113], v[0:1]
	v_mov_b64_e32 v[140:141], v[12:13]
	v_mov_b64_e32 v[138:139], v[10:11]
	v_mov_b64_e32 v[136:137], v[8:9]
	v_mov_b64_e32 v[134:135], v[6:7]
	v_mov_b64_e32 v[132:133], v[4:5]
	v_mov_b64_e32 v[130:131], v[2:3]
	v_mov_b64_e32 v[128:129], v[0:1]
	v_mov_b64_e32 v[156:157], v[12:13]
	v_mov_b64_e32 v[154:155], v[10:11]
	v_mov_b64_e32 v[152:153], v[8:9]
	v_mov_b64_e32 v[150:151], v[6:7]
	v_mov_b64_e32 v[148:149], v[4:5]
	v_mov_b64_e32 v[146:147], v[2:3]
	v_mov_b64_e32 v[144:145], v[0:1]
	s_waitcnt lgkmcnt(0)
	s_barrier
	ds_read_b128 v[180:183], v211
	ds_read_b128 v[184:187], v219
	ds_read_b128 v[188:191], v220
	ds_read_b128 v[192:195], v221
	ds_read_b128 v[196:199], v222
	ds_read_b128 v[236:239], v223
	ds_read_b128 v[240:243], v224
	ds_read_b128 v[244:247], v225
	s_waitcnt lgkmcnt(0)
	v_mov_b32_e32 v220, 0
.LBB0_298:
	s_cmp_gt_u32 s97, s15
	s_cbranch_scc1 .Lattn_skip0
	v_add_u32_e32 v0, s40, v206
	ds_read_b128 v[144:147], v0
	ds_read_b128 v[148:151], v0 offset:32
	ds_read_b128 v[152:155], v0 offset:64
	ds_read_b128 v[156:159], v0 offset:96
	s_waitcnt vmcnt(2)
	v_add_co_u32_e32 v6, vcc, 0x20000, v200
	v_lshl_add_u64 v[14:15], v[202:203], 0, s[26:27]
	s_nop 0
	v_addc_co_u32_e32 v7, vcc, 0, v201, vcc
	s_waitcnt vmcnt(1)
	v_add_co_u32_e32 v10, vcc, 0x4000, v14
	global_load_dwordx4 v[2:5], v[6:7], off
	s_nop 0
	global_load_dwordx4 v[6:9], v[6:7], off offset:256
	v_addc_co_u32_e32 v11, vcc, 0, v15, vcc
	v_add_co_u32_e32 v160, vcc, 0x6000, v14
	s_nop 0
	v_addc_co_u32_e32 v161, vcc, 0, v15, vcc
	global_load_dwordx4 v[10:13], v[10:11], off
	s_nop 0
	global_load_dwordx4 v[176:179], v[160:161], off
	s_waitcnt lgkmcnt(3)
	v_mfma_f32_32x32x16_bf16 v[160:175], v[144:147], v[180:183], 0
	ds_read_b128 v[144:147], v0 offset:128
	s_waitcnt lgkmcnt(3)
	v_mfma_f32_32x32x16_bf16 v[160:175], v[148:151], v[184:187], v[160:175]
	ds_read_b128 v[148:151], v0 offset:160
	s_waitcnt lgkmcnt(3)
	v_mfma_f32_32x32x16_bf16 v[160:175], v[152:155], v[188:191], v[160:175]
	ds_read_b128 v[152:155], v0 offset:192
	s_waitcnt lgkmcnt(3)
	v_mfma_f32_32x32x16_bf16 v[160:175], v[156:159], v[192:195], v[160:175]
	ds_read_b128 v[156:159], v0 offset:224
	s_waitcnt lgkmcnt(3)
	v_mfma_f32_32x32x16_bf16 v[160:175], v[144:147], v[196:199], v[160:175]
	s_waitcnt lgkmcnt(2)
	v_mfma_f32_32x32x16_bf16 v[160:175], v[148:151], v[236:239], v[160:175]
	s_waitcnt lgkmcnt(1)
	v_mfma_f32_32x32x16_bf16 v[160:175], v[152:155], v[240:243], v[160:175]
	s_waitcnt lgkmcnt(0)
	v_mfma_f32_32x32x16_bf16 v[160:175], v[156:159], v[244:247], v[160:175]
	ds_read_b128 v[144:147], v218 offset:17408
	ds_read_b128 v[148:151], v218 offset:17440
	ds_read_b128 v[152:155], v218 offset:19968
	s_nop 8
	v_add_f32_e32 v160, v220, v160
	v_add_f32_e32 v161, v220, v161
	v_add_f32_e32 v162, v220, v162
	v_add_f32_e32 v163, v220, v163
	v_add_f32_e32 v164, v220, v164
	v_add_f32_e32 v165, v220, v165
	v_add_f32_e32 v166, v220, v166
	v_add_f32_e32 v167, v220, v167
	v_add_f32_e32 v168, v220, v168
	v_add_f32_e32 v169, v220, v169
	v_add_f32_e32 v170, v220, v170
	v_add_f32_e32 v171, v220, v171
	v_add_f32_e32 v172, v220, v172
	v_add_f32_e32 v173, v220, v173
	v_add_f32_e32 v174, v220, v174
	v_add_f32_e32 v175, v220, v175
	s_cmp_lg_u32 s90, s26
	s_cbranch_scc1 .LBB0_301
	s_nop 6
	v_cndmask_b32_e64 v0, v160, v215, s[42:43]
	v_cndmask_b32_e64 v160, v0, v160, s[44:45]
	v_cndmask_b32_e64 v0, v164, v215, s[50:51]
	v_cndmask_b32_e64 v164, v0, v164, s[52:53]
	v_cndmask_b32_e64 v0, v168, v215, s[58:59]
	v_cndmask_b32_e64 v168, v0, v168, s[60:61]
	v_cndmask_b32_e64 v0, v172, v215, s[66:67]
	v_cndmask_b32_e64 v161, v215, v161, s[44:45]
	v_cndmask_b32_e64 v162, v162, v215, s[46:47]
	v_cndmask_b32_e64 v163, v163, v215, s[48:49]
	v_cndmask_b32_e64 v165, v215, v165, s[52:53]
	v_cndmask_b32_e64 v166, v166, v215, s[54:55]
	v_cndmask_b32_e64 v167, v167, v215, s[56:57]
	v_cndmask_b32_e64 v169, v215, v169, s[60:61]
	v_cndmask_b32_e64 v170, v170, v215, s[62:63]
	v_cndmask_b32_e64 v171, v171, v215, s[64:65]
	v_cndmask_b32_e64 v173, v215, v173, s[68:69]
	v_cndmask_b32_e64 v172, v0, v172, s[68:69]
	v_cndmask_b32_e64 v174, v174, v215, s[70:71]
	v_cndmask_b32_e64 v175, v175, v215, s[72:73]
.LBB0_301:
	s_nop 6
	v_max_f32_e32 v0, v161, v161
	v_max_f32_e32 v224, v160, v160
	v_max_f32_e32 v0, v224, v0
	v_max3_f32 v0, v0, v162, v163
	v_max3_f32 v0, v0, v164, v165
	v_max3_f32 v0, v0, v166, v167
	v_max3_f32 v0, v0, v168, v169
	v_max3_f32 v0, v0, v170, v171
	v_max3_f32 v0, v0, v172, v173
	v_max3_f32 v0, v0, v174, v175
	v_mov_b32_e32 v224, v0
	s_nop 1
	v_permlane32_swap_b32_e32 v0, v224
	v_max_f32_e32 v224, v224, v224
	v_max_f32_e32 v0, v0, v0
	v_max_f32_e32 v0, v0, v224
	s_cmp_eq_u32 s26, 0
	s_cselect_b64 s[30:31], -1, 0
	s_cmp_lg_u32 s26, 0
	v_cmp_lt_f32_e32 vcc, s1, v0
	s_cbranch_scc0 .LBB0_303
	s_cmp_lg_u64 vcc, 0
	s_cselect_b64 s[94:95], -1, 0
	s_cbranch_execz .LBB0_304
	s_branch .LBB0_305

.LBB0_305:
	s_andn2_b64 vcc, exec, s[94:95]
	s_cbranch_vccnz .LBB0_307
	v_cmp_lt_f32_e32 vcc, s1, v0
	s_or_b64 vcc, s[30:31], vcc
	s_nop 0
	v_cndmask_b32_e32 v222, 0, v0, vcc
	v_exp_f32_e64 v0, -v222
	v_add_f32_e32 v232, v232, v222
	v_xor_b32_e32 v220, 0x80000000, v232
	v_pk_add_f32 v[160:161], v[160:161], v[222:223] op_sel_hi:[1,0] neg_lo:[0,1] neg_hi:[0,1]
	v_pk_add_f32 v[162:163], v[162:163], v[222:223] op_sel_hi:[1,0] neg_lo:[0,1] neg_hi:[0,1]
	v_pk_add_f32 v[164:165], v[164:165], v[222:223] op_sel_hi:[1,0] neg_lo:[0,1] neg_hi:[0,1]
	v_pk_add_f32 v[166:167], v[166:167], v[222:223] op_sel_hi:[1,0] neg_lo:[0,1] neg_hi:[0,1]
	v_pk_add_f32 v[168:169], v[168:169], v[222:223] op_sel_hi:[1,0] neg_lo:[0,1] neg_hi:[0,1]
	v_pk_add_f32 v[170:171], v[170:171], v[222:223] op_sel_hi:[1,0] neg_lo:[0,1] neg_hi:[0,1]
	v_pk_add_f32 v[172:173], v[172:173], v[222:223] op_sel_hi:[1,0] neg_lo:[0,1] neg_hi:[0,1]
	v_pk_add_f32 v[174:175], v[174:175], v[222:223] op_sel_hi:[1,0] neg_lo:[0,1] neg_hi:[0,1]
	v_pk_mul_f32 v[142:143], v[142:143], v[0:1] op_sel_hi:[1,0]
	v_pk_mul_f32 v[140:141], v[140:141], v[0:1] op_sel_hi:[1,0]
	v_pk_mul_f32 v[138:139], v[138:139], v[0:1] op_sel_hi:[1,0]
	v_pk_mul_f32 v[136:137], v[136:137], v[0:1] op_sel_hi:[1,0]
	v_pk_mul_f32 v[134:135], v[134:135], v[0:1] op_sel_hi:[1,0]
	v_pk_mul_f32 v[132:133], v[132:133], v[0:1] op_sel_hi:[1,0]
	v_pk_mul_f32 v[130:131], v[130:131], v[0:1] op_sel_hi:[1,0]
	v_pk_mul_f32 v[128:129], v[128:129], v[0:1] op_sel_hi:[1,0]
	v_pk_mul_f32 v[126:127], v[126:127], v[0:1] op_sel_hi:[1,0]
	v_pk_mul_f32 v[124:125], v[124:125], v[0:1] op_sel_hi:[1,0]
	v_pk_mul_f32 v[122:123], v[122:123], v[0:1] op_sel_hi:[1,0]
	v_pk_mul_f32 v[120:121], v[120:121], v[0:1] op_sel_hi:[1,0]
	v_pk_mul_f32 v[118:119], v[118:119], v[0:1] op_sel_hi:[1,0]
	v_pk_mul_f32 v[116:117], v[116:117], v[0:1] op_sel_hi:[1,0]
	v_pk_mul_f32 v[114:115], v[114:115], v[0:1] op_sel_hi:[1,0]
	v_pk_mul_f32 v[112:113], v[112:113], v[0:1] op_sel_hi:[1,0]
	v_pk_mul_f32 v[110:111], v[110:111], v[0:1] op_sel_hi:[1,0]
	v_pk_mul_f32 v[108:109], v[108:109], v[0:1] op_sel_hi:[1,0]
	v_pk_mul_f32 v[106:107], v[106:107], v[0:1] op_sel_hi:[1,0]
	v_pk_mul_f32 v[104:105], v[104:105], v[0:1] op_sel_hi:[1,0]
	v_pk_mul_f32 v[102:103], v[102:103], v[0:1] op_sel_hi:[1,0]
	v_pk_mul_f32 v[100:101], v[100:101], v[0:1] op_sel_hi:[1,0]
	v_pk_mul_f32 v[98:99], v[98:99], v[0:1] op_sel_hi:[1,0]
	v_pk_mul_f32 v[96:97], v[96:97], v[0:1] op_sel_hi:[1,0]
	v_pk_mul_f32 v[94:95], v[94:95], v[0:1] op_sel_hi:[1,0]
	v_pk_mul_f32 v[92:93], v[92:93], v[0:1] op_sel_hi:[1,0]
	v_pk_mul_f32 v[90:91], v[90:91], v[0:1] op_sel_hi:[1,0]
	v_pk_mul_f32 v[88:89], v[88:89], v[0:1] op_sel_hi:[1,0]
	v_pk_mul_f32 v[86:87], v[86:87], v[0:1] op_sel_hi:[1,0]
	v_pk_mul_f32 v[84:85], v[84:85], v[0:1] op_sel_hi:[1,0]
	v_pk_mul_f32 v[82:83], v[82:83], v[0:1] op_sel_hi:[1,0]
	v_pk_mul_f32 v[80:81], v[80:81], v[0:1] op_sel_hi:[1,0]
	v_pk_mul_f32 v[78:79], v[78:79], v[0:1] op_sel_hi:[1,0]
	v_pk_mul_f32 v[76:77], v[76:77], v[0:1] op_sel_hi:[1,0]
	v_pk_mul_f32 v[74:75], v[74:75], v[0:1] op_sel_hi:[1,0]
	v_pk_mul_f32 v[72:73], v[72:73], v[0:1] op_sel_hi:[1,0]
	v_pk_mul_f32 v[70:71], v[70:71], v[0:1] op_sel_hi:[1,0]
	v_pk_mul_f32 v[68:69], v[68:69], v[0:1] op_sel_hi:[1,0]
	v_pk_mul_f32 v[66:67], v[66:67], v[0:1] op_sel_hi:[1,0]
	v_pk_mul_f32 v[64:65], v[64:65], v[0:1] op_sel_hi:[1,0]
	v_pk_mul_f32 v[62:63], v[62:63], v[0:1] op_sel_hi:[1,0]
	v_pk_mul_f32 v[60:61], v[60:61], v[0:1] op_sel_hi:[1,0]
	v_pk_mul_f32 v[58:59], v[58:59], v[0:1] op_sel_hi:[1,0]
	v_pk_mul_f32 v[56:57], v[56:57], v[0:1] op_sel_hi:[1,0]
	v_pk_mul_f32 v[54:55], v[54:55], v[0:1] op_sel_hi:[1,0]
	v_pk_mul_f32 v[52:53], v[52:53], v[0:1] op_sel_hi:[1,0]
	v_pk_mul_f32 v[50:51], v[50:51], v[0:1] op_sel_hi:[1,0]
	v_pk_mul_f32 v[48:49], v[48:49], v[0:1] op_sel_hi:[1,0]
	v_pk_mul_f32 v[46:47], v[46:47], v[0:1] op_sel_hi:[1,0]
	v_pk_mul_f32 v[44:45], v[44:45], v[0:1] op_sel_hi:[1,0]
	v_pk_mul_f32 v[42:43], v[42:43], v[0:1] op_sel_hi:[1,0]
	v_pk_mul_f32 v[40:41], v[40:41], v[0:1] op_sel_hi:[1,0]
	v_pk_mul_f32 v[38:39], v[38:39], v[0:1] op_sel_hi:[1,0]
	v_pk_mul_f32 v[36:37], v[36:37], v[0:1] op_sel_hi:[1,0]
	v_pk_mul_f32 v[34:35], v[34:35], v[0:1] op_sel_hi:[1,0]
	v_pk_mul_f32 v[32:33], v[32:33], v[0:1] op_sel_hi:[1,0]
	v_pk_mul_f32 v[30:31], v[30:31], v[0:1] op_sel_hi:[1,0]
	v_pk_mul_f32 v[28:29], v[28:29], v[0:1] op_sel_hi:[1,0]
	v_pk_mul_f32 v[26:27], v[26:27], v[0:1] op_sel_hi:[1,0]
	v_pk_mul_f32 v[24:25], v[24:25], v[0:1] op_sel_hi:[1,0]
	v_pk_mul_f32 v[22:23], v[22:23], v[0:1] op_sel_hi:[1,0]
	v_pk_mul_f32 v[20:21], v[20:21], v[0:1] op_sel_hi:[1,0]
	v_pk_mul_f32 v[18:19], v[18:19], v[0:1] op_sel_hi:[1,0]
	v_pk_mul_f32 v[16:17], v[16:17], v[0:1] op_sel_hi:[1,0]
	v_mul_f32_e32 v235, v235, v0
.LBB0_307:
	v_exp_f32_e32 v0, v160
	v_exp_f32_e32 v160, v161
	v_exp_f32_e32 v161, v162
	v_exp_f32_e32 v162, v163
	v_add_f32_e32 v163, 0, v0
	v_exp_f32_e32 v164, v164
	v_add_f32_e32 v163, v160, v163
	v_exp_f32_e32 v165, v165
	v_add_f32_e32 v163, v161, v163
	v_exp_f32_e32 v166, v166
	v_add_f32_e32 v163, v162, v163
	v_exp_f32_e32 v167, v167
	v_add_f32_e32 v163, v164, v163
	v_exp_f32_e32 v168, v168
	v_add_f32_e32 v163, v165, v163
	v_exp_f32_e32 v169, v169
	v_add_f32_e32 v163, v166, v163
	v_exp_f32_e32 v170, v170
	v_add_f32_e32 v163, v167, v163
	v_exp_f32_e32 v171, v171
	v_add_f32_e32 v163, v168, v163
	v_exp_f32_e32 v172, v172
	v_add_f32_e32 v163, v169, v163
	v_exp_f32_e32 v173, v173
	v_add_f32_e32 v163, v170, v163
	v_exp_f32_e32 v174, v174
	v_add_f32_e32 v163, v171, v163
	v_exp_f32_e32 v175, v175
	v_add_f32_e32 v163, v172, v163
	v_add_f32_e32 v163, v173, v163
	v_add_f32_e32 v163, v174, v163
	v_add_f32_e32 v224, v175, v163
	v_cvt_pk_bf16_f32 v160, v0, v160
	v_cvt_pk_bf16_f32 v161, v161, v162
	v_cvt_pk_bf16_f32 v162, v164, v165
	v_cvt_pk_bf16_f32 v163, v166, v167
	v_cvt_pk_bf16_f32 v164, v168, v169
	v_cvt_pk_bf16_f32 v165, v170, v171
	v_cvt_pk_bf16_f32 v166, v172, v173
	v_cvt_pk_bf16_f32 v167, v174, v175
	ds_read_b128 v[168:171], v218 offset:20000
	s_waitcnt lgkmcnt(3)
	v_mfma_f32_32x32x16_bf16 v[128:143], v[144:147], v[160:163], v[128:143]
	ds_read_b128 v[172:175], v218 offset:22528
	s_waitcnt lgkmcnt(3)
	v_mfma_f32_32x32x16_bf16 v[128:143], v[148:151], v[164:167], v[128:143]
	ds_read_b128 v[148:151], v218 offset:22560
	s_waitcnt lgkmcnt(3)
	v_mfma_f32_32x32x16_bf16 v[112:127], v[152:155], v[160:163], v[112:127]
	ds_read_b128 v[152:155], v218 offset:25088
	s_waitcnt lgkmcnt(3)
	v_mfma_f32_32x32x16_bf16 v[112:127], v[168:171], v[164:167], v[112:127]
	ds_read_b128 v[168:171], v218 offset:25120
	s_waitcnt lgkmcnt(3)
	v_mfma_f32_32x32x16_bf16 v[96:111], v[172:175], v[160:163], v[96:111]
	ds_read_b128 v[172:175], v218 offset:27648
	s_waitcnt lgkmcnt(3)
	v_mfma_f32_32x32x16_bf16 v[96:111], v[148:151], v[164:167], v[96:111]
	ds_read_b128 v[148:151], v218 offset:27680
	s_waitcnt lgkmcnt(3)
	v_mfma_f32_32x32x16_bf16 v[80:95], v[152:155], v[160:163], v[80:95]
	ds_read_b128 v[152:155], v218 offset:30208
	s_waitcnt lgkmcnt(3)
	v_mfma_f32_32x32x16_bf16 v[80:95], v[168:171], v[164:167], v[80:95]
	ds_read_b128 v[168:171], v218 offset:30240
	s_waitcnt lgkmcnt(3)
	v_mfma_f32_32x32x16_bf16 v[64:79], v[172:175], v[160:163], v[64:79]
	ds_read_b128 v[172:175], v218 offset:32768
	s_waitcnt lgkmcnt(3)
	v_mfma_f32_32x32x16_bf16 v[64:79], v[148:151], v[164:167], v[64:79]
	ds_read_b128 v[148:151], v218 offset:32800
	s_waitcnt lgkmcnt(3)
	v_mfma_f32_32x32x16_bf16 v[48:63], v[152:155], v[160:163], v[48:63]
	ds_read_b128 v[152:155], v218 offset:35328
	s_waitcnt lgkmcnt(3)
	v_mfma_f32_32x32x16_bf16 v[48:63], v[168:171], v[164:167], v[48:63]
	ds_read_b128 v[168:171], v218 offset:35360
	s_waitcnt vmcnt(3)
	ds_write_b128 v207, v[2:5] offset:37888
	s_waitcnt vmcnt(2)
	ds_write_b128 v207, v[6:9] offset:46592
	s_waitcnt vmcnt(1)
	ds_write2_b64 v210, v[10:11], v[12:13] offset1:2
	s_waitcnt vmcnt(0)
	ds_write2_b64 v234, v[176:177], v[178:179] offset1:2
	s_waitcnt lgkmcnt(7)
	v_mfma_f32_32x32x16_bf16 v[32:47], v[172:175], v[160:163], v[32:47]
	s_waitcnt lgkmcnt(6)
	v_mfma_f32_32x32x16_bf16 v[32:47], v[148:151], v[164:167], v[32:47]
	s_waitcnt lgkmcnt(5)
	v_mfma_f32_32x32x16_bf16 v[16:31], v[152:155], v[160:163], v[16:31]
	s_waitcnt lgkmcnt(4)
	v_mfma_f32_32x32x16_bf16 v[16:31], v[168:171], v[164:167], v[16:31]
	v_add_f32_e32 v235, v235, v224
	s_add_i32 s78, s97, 2
	s_cmp_lt_u32 s78, s77
	s_cselect_b64 s[94:95], -1, 0
	s_cmp_ge_u32 s78, s77
	s_cselect_b64 s[30:31], -1, 0
	s_and_b64 vcc, exec, s[30:31]
	s_branch .Lattn_w0_done

.LBB0_314:
	s_cmp_ge_u32 s97, s15
	s_cbranch_scc1 .Lattn_skip1
	ds_read_b128 v[144:147], v233 offset:37888
	ds_read_b128 v[148:151], v233 offset:37920
	ds_read_b128 v[152:155], v233 offset:37952
	ds_read_b128 v[156:159], v233 offset:37984
	v_add_co_u32_e32 v6, vcc, 0x40000, v200
	s_nop 1
	v_addc_co_u32_e32 v7, vcc, 0, v201, vcc
	v_add_co_u32_e32 v10, vcc, 0x8000, v14
	global_load_dwordx4 v[2:5], v[6:7], off
	s_nop 0
	global_load_dwordx4 v[6:9], v[6:7], off offset:256
	v_addc_co_u32_e32 v11, vcc, 0, v15, vcc
	v_add_co_u32_e32 v14, vcc, 0xa000, v14
	s_nop 1
	v_addc_co_u32_e32 v15, vcc, 0, v15, vcc
	global_load_dwordx4 v[10:13], v[10:11], off
	s_nop 0
	global_load_dwordx4 v[176:179], v[14:15], off
	s_branch .Lattn_qk1_rest

.LBB0_315:
	ds_read_b128 v[144:147], v233 offset:37888
	ds_read_b128 v[148:151], v233 offset:37920
	ds_read_b128 v[152:155], v233 offset:37952
	ds_read_b128 v[156:159], v233 offset:37984
.Lattn_qk1_rest:
	s_waitcnt lgkmcnt(3)
	v_mfma_f32_32x32x16_bf16 v[160:175], v[144:147], v[180:183], 0
	ds_read_b128 v[144:147], v233 offset:38016
	s_waitcnt lgkmcnt(3)
	v_mfma_f32_32x32x16_bf16 v[160:175], v[148:151], v[184:187], v[160:175]
	ds_read_b128 v[148:151], v233 offset:38048
	s_waitcnt lgkmcnt(3)
	v_mfma_f32_32x32x16_bf16 v[160:175], v[152:155], v[188:191], v[160:175]
	ds_read_b128 v[152:155], v233 offset:38080
	s_waitcnt lgkmcnt(3)
	v_mfma_f32_32x32x16_bf16 v[160:175], v[156:159], v[192:195], v[160:175]
	ds_read_b128 v[156:159], v233 offset:38112
	s_waitcnt lgkmcnt(3)
	v_mfma_f32_32x32x16_bf16 v[160:175], v[144:147], v[196:199], v[160:175]
	s_waitcnt lgkmcnt(2)
	v_mfma_f32_32x32x16_bf16 v[160:175], v[148:151], v[236:239], v[160:175]
	s_waitcnt lgkmcnt(1)
	v_mfma_f32_32x32x16_bf16 v[160:175], v[152:155], v[240:243], v[160:175]
	s_waitcnt lgkmcnt(0)
	v_mfma_f32_32x32x16_bf16 v[160:175], v[156:159], v[244:247], v[160:175]
	ds_read_b128 v[144:147], v218 offset:55296
	ds_read_b128 v[148:151], v218 offset:55328
	ds_read_b128 v[152:155], v218 offset:57856
	s_nop 8
	v_add_f32_e32 v160, v220, v160
	v_add_f32_e32 v161, v220, v161
	v_add_f32_e32 v162, v220, v162
	v_add_f32_e32 v163, v220, v163
	v_add_f32_e32 v164, v220, v164
	v_add_f32_e32 v165, v220, v165
	v_add_f32_e32 v166, v220, v166
	v_add_f32_e32 v167, v220, v167
	v_add_f32_e32 v168, v220, v168
	v_add_f32_e32 v169, v220, v169
	v_add_f32_e32 v170, v220, v170
	v_add_f32_e32 v171, v220, v171
	v_add_f32_e32 v172, v220, v172
	v_add_f32_e32 v173, v220, v173
	v_add_f32_e32 v174, v220, v174
	v_add_f32_e32 v175, v220, v175
	s_cmp_lg_u32 s96, s26
	s_cbranch_scc1 .LBB0_317
	s_nop 6
	v_cndmask_b32_e64 v0, v160, v215, s[42:43]
	v_cndmask_b32_e64 v160, v0, v160, s[44:45]
	v_cndmask_b32_e64 v0, v164, v215, s[50:51]
	v_cndmask_b32_e64 v164, v0, v164, s[52:53]
	v_cndmask_b32_e64 v0, v168, v215, s[58:59]
	v_cndmask_b32_e64 v168, v0, v168, s[60:61]
	v_cndmask_b32_e64 v0, v172, v215, s[66:67]
	v_cndmask_b32_e64 v161, v215, v161, s[44:45]
	v_cndmask_b32_e64 v162, v162, v215, s[46:47]
	v_cndmask_b32_e64 v163, v163, v215, s[48:49]
	v_cndmask_b32_e64 v165, v215, v165, s[52:53]
	v_cndmask_b32_e64 v166, v166, v215, s[54:55]
	v_cndmask_b32_e64 v167, v167, v215, s[56:57]
	v_cndmask_b32_e64 v169, v215, v169, s[60:61]
	v_cndmask_b32_e64 v170, v170, v215, s[62:63]
	v_cndmask_b32_e64 v171, v171, v215, s[64:65]
	v_cndmask_b32_e64 v173, v215, v173, s[68:69]
	v_cndmask_b32_e64 v172, v0, v172, s[68:69]
	v_cndmask_b32_e64 v174, v174, v215, s[70:71]
	v_cndmask_b32_e64 v175, v175, v215, s[72:73]
.LBB0_317:
	s_nop 6
	v_max_f32_e32 v0, v161, v161
	v_max_f32_e32 v14, v160, v160
	v_max_f32_e32 v0, v14, v0
	v_max3_f32 v0, v0, v162, v163
	v_max3_f32 v0, v0, v164, v165
	v_max3_f32 v0, v0, v166, v167
	v_max3_f32 v0, v0, v168, v169
	v_max3_f32 v0, v0, v170, v171
	v_max3_f32 v0, v0, v172, v173
	v_max3_f32 v0, v0, v174, v175
	v_mov_b32_e32 v14, v0
	s_nop 1
	v_permlane32_swap_b32_e32 v0, v14
	v_max_f32_e32 v14, v14, v14
	v_max_f32_e32 v0, v0, v0
	v_max_f32_e32 v0, v0, v14
	v_cmp_lt_f32_e32 vcc, s1, v0
	s_cbranch_vccz .LBB0_319
	s_nop 0
	v_cndmask_b32_e32 v14, 0, v0, vcc
	v_exp_f32_e64 v0, -v14
	v_add_f32_e32 v232, v232, v14
	v_xor_b32_e32 v220, 0x80000000, v232
	v_pk_add_f32 v[160:161], v[160:161], v[14:15] op_sel_hi:[1,0] neg_lo:[0,1] neg_hi:[0,1]
	v_pk_add_f32 v[162:163], v[162:163], v[14:15] op_sel_hi:[1,0] neg_lo:[0,1] neg_hi:[0,1]
	v_pk_add_f32 v[164:165], v[164:165], v[14:15] op_sel_hi:[1,0] neg_lo:[0,1] neg_hi:[0,1]
	v_pk_add_f32 v[166:167], v[166:167], v[14:15] op_sel_hi:[1,0] neg_lo:[0,1] neg_hi:[0,1]
	v_pk_add_f32 v[168:169], v[168:169], v[14:15] op_sel_hi:[1,0] neg_lo:[0,1] neg_hi:[0,1]
	v_pk_add_f32 v[170:171], v[170:171], v[14:15] op_sel_hi:[1,0] neg_lo:[0,1] neg_hi:[0,1]
	v_pk_add_f32 v[172:173], v[172:173], v[14:15] op_sel_hi:[1,0] neg_lo:[0,1] neg_hi:[0,1]
	v_pk_add_f32 v[174:175], v[174:175], v[14:15] op_sel_hi:[1,0] neg_lo:[0,1] neg_hi:[0,1]
	v_pk_mul_f32 v[142:143], v[142:143], v[0:1] op_sel_hi:[1,0]
	v_pk_mul_f32 v[140:141], v[140:141], v[0:1] op_sel_hi:[1,0]
	v_pk_mul_f32 v[138:139], v[138:139], v[0:1] op_sel_hi:[1,0]
	v_pk_mul_f32 v[136:137], v[136:137], v[0:1] op_sel_hi:[1,0]
	v_pk_mul_f32 v[134:135], v[134:135], v[0:1] op_sel_hi:[1,0]
	v_pk_mul_f32 v[132:133], v[132:133], v[0:1] op_sel_hi:[1,0]
	v_pk_mul_f32 v[130:131], v[130:131], v[0:1] op_sel_hi:[1,0]
	v_pk_mul_f32 v[128:129], v[128:129], v[0:1] op_sel_hi:[1,0]
	v_pk_mul_f32 v[126:127], v[126:127], v[0:1] op_sel_hi:[1,0]
	v_pk_mul_f32 v[124:125], v[124:125], v[0:1] op_sel_hi:[1,0]
	v_pk_mul_f32 v[122:123], v[122:123], v[0:1] op_sel_hi:[1,0]
	v_pk_mul_f32 v[120:121], v[120:121], v[0:1] op_sel_hi:[1,0]
	v_pk_mul_f32 v[118:119], v[118:119], v[0:1] op_sel_hi:[1,0]
	v_pk_mul_f32 v[116:117], v[116:117], v[0:1] op_sel_hi:[1,0]
	v_pk_mul_f32 v[114:115], v[114:115], v[0:1] op_sel_hi:[1,0]
	v_pk_mul_f32 v[112:113], v[112:113], v[0:1] op_sel_hi:[1,0]
	v_pk_mul_f32 v[110:111], v[110:111], v[0:1] op_sel_hi:[1,0]
	v_pk_mul_f32 v[108:109], v[108:109], v[0:1] op_sel_hi:[1,0]
	v_pk_mul_f32 v[106:107], v[106:107], v[0:1] op_sel_hi:[1,0]
	v_pk_mul_f32 v[104:105], v[104:105], v[0:1] op_sel_hi:[1,0]
	v_pk_mul_f32 v[102:103], v[102:103], v[0:1] op_sel_hi:[1,0]
	v_pk_mul_f32 v[100:101], v[100:101], v[0:1] op_sel_hi:[1,0]
	v_pk_mul_f32 v[98:99], v[98:99], v[0:1] op_sel_hi:[1,0]
	v_pk_mul_f32 v[96:97], v[96:97], v[0:1] op_sel_hi:[1,0]
	v_pk_mul_f32 v[94:95], v[94:95], v[0:1] op_sel_hi:[1,0]
	v_pk_mul_f32 v[92:93], v[92:93], v[0:1] op_sel_hi:[1,0]
	v_pk_mul_f32 v[90:91], v[90:91], v[0:1] op_sel_hi:[1,0]
	v_pk_mul_f32 v[88:89], v[88:89], v[0:1] op_sel_hi:[1,0]
	v_pk_mul_f32 v[86:87], v[86:87], v[0:1] op_sel_hi:[1,0]
	v_pk_mul_f32 v[84:85], v[84:85], v[0:1] op_sel_hi:[1,0]
	v_pk_mul_f32 v[82:83], v[82:83], v[0:1] op_sel_hi:[1,0]
	v_pk_mul_f32 v[80:81], v[80:81], v[0:1] op_sel_hi:[1,0]
	v_pk_mul_f32 v[78:79], v[78:79], v[0:1] op_sel_hi:[1,0]
	v_pk_mul_f32 v[76:77], v[76:77], v[0:1] op_sel_hi:[1,0]
	v_pk_mul_f32 v[74:75], v[74:75], v[0:1] op_sel_hi:[1,0]
	v_pk_mul_f32 v[72:73], v[72:73], v[0:1] op_sel_hi:[1,0]
	v_pk_mul_f32 v[70:71], v[70:71], v[0:1] op_sel_hi:[1,0]
	v_pk_mul_f32 v[68:69], v[68:69], v[0:1] op_sel_hi:[1,0]
	v_pk_mul_f32 v[66:67], v[66:67], v[0:1] op_sel_hi:[1,0]
	v_pk_mul_f32 v[64:65], v[64:65], v[0:1] op_sel_hi:[1,0]
	v_pk_mul_f32 v[62:63], v[62:63], v[0:1] op_sel_hi:[1,0]
	v_pk_mul_f32 v[60:61], v[60:61], v[0:1] op_sel_hi:[1,0]
	v_pk_mul_f32 v[58:59], v[58:59], v[0:1] op_sel_hi:[1,0]
	v_pk_mul_f32 v[56:57], v[56:57], v[0:1] op_sel_hi:[1,0]
	v_pk_mul_f32 v[54:55], v[54:55], v[0:1] op_sel_hi:[1,0]
	v_pk_mul_f32 v[52:53], v[52:53], v[0:1] op_sel_hi:[1,0]
	v_pk_mul_f32 v[50:51], v[50:51], v[0:1] op_sel_hi:[1,0]
	v_pk_mul_f32 v[48:49], v[48:49], v[0:1] op_sel_hi:[1,0]
	v_pk_mul_f32 v[46:47], v[46:47], v[0:1] op_sel_hi:[1,0]
	v_pk_mul_f32 v[44:45], v[44:45], v[0:1] op_sel_hi:[1,0]
	v_pk_mul_f32 v[42:43], v[42:43], v[0:1] op_sel_hi:[1,0]
	v_pk_mul_f32 v[40:41], v[40:41], v[0:1] op_sel_hi:[1,0]
	v_pk_mul_f32 v[38:39], v[38:39], v[0:1] op_sel_hi:[1,0]
	v_pk_mul_f32 v[36:37], v[36:37], v[0:1] op_sel_hi:[1,0]
	v_pk_mul_f32 v[34:35], v[34:35], v[0:1] op_sel_hi:[1,0]
	v_pk_mul_f32 v[32:33], v[32:33], v[0:1] op_sel_hi:[1,0]
	v_pk_mul_f32 v[30:31], v[30:31], v[0:1] op_sel_hi:[1,0]
	v_pk_mul_f32 v[28:29], v[28:29], v[0:1] op_sel_hi:[1,0]
	v_pk_mul_f32 v[26:27], v[26:27], v[0:1] op_sel_hi:[1,0]
	v_pk_mul_f32 v[24:25], v[24:25], v[0:1] op_sel_hi:[1,0]
	v_pk_mul_f32 v[22:23], v[22:23], v[0:1] op_sel_hi:[1,0]
	v_pk_mul_f32 v[20:21], v[20:21], v[0:1] op_sel_hi:[1,0]
	v_pk_mul_f32 v[18:19], v[18:19], v[0:1] op_sel_hi:[1,0]
	v_pk_mul_f32 v[16:17], v[16:17], v[0:1] op_sel_hi:[1,0]
	v_mul_f32_e32 v235, v235, v0
.LBB0_319:
	v_exp_f32_e32 v0, v160
	v_exp_f32_e32 v14, v161
	v_exp_f32_e32 v15, v162
	v_exp_f32_e32 v161, v163
	v_add_f32_e32 v160, 0, v0
	v_exp_f32_e32 v162, v164
	v_add_f32_e32 v160, v14, v160
	v_exp_f32_e32 v163, v165
	v_add_f32_e32 v160, v15, v160
	v_exp_f32_e32 v164, v166
	v_add_f32_e32 v160, v161, v160
	v_exp_f32_e32 v165, v167
	v_add_f32_e32 v160, v162, v160
	v_exp_f32_e32 v166, v168
	v_add_f32_e32 v160, v163, v160
	v_exp_f32_e32 v167, v169
	v_add_f32_e32 v160, v164, v160
	v_exp_f32_e32 v168, v170
	v_add_f32_e32 v160, v165, v160
	v_exp_f32_e32 v169, v171
	v_add_f32_e32 v160, v166, v160
	v_exp_f32_e32 v170, v172
	v_add_f32_e32 v160, v167, v160
	v_exp_f32_e32 v171, v173
	v_add_f32_e32 v160, v168, v160
	v_exp_f32_e32 v172, v174
	v_add_f32_e32 v160, v169, v160
	v_exp_f32_e32 v173, v175
	v_add_f32_e32 v160, v170, v160
	v_add_f32_e32 v160, v171, v160
	v_add_f32_e32 v160, v172, v160
	v_add_f32_e32 v224, v173, v160
	v_cvt_pk_bf16_f32 v160, v0, v14
	v_cvt_pk_bf16_f32 v161, v15, v161
	v_cvt_pk_bf16_f32 v162, v162, v163
	v_cvt_pk_bf16_f32 v163, v164, v165
	v_cvt_pk_bf16_f32 v164, v166, v167
	v_cvt_pk_bf16_f32 v165, v168, v169
	v_cvt_pk_bf16_f32 v166, v170, v171
	v_cvt_pk_bf16_f32 v167, v172, v173
	ds_read_b128 v[168:171], v218 offset:57888
	s_waitcnt lgkmcnt(3)
	v_mfma_f32_32x32x16_bf16 v[128:143], v[144:147], v[160:163], v[128:143]
	ds_read_b128 v[172:175], v218 offset:60416
	s_waitcnt lgkmcnt(3)
	v_mfma_f32_32x32x16_bf16 v[128:143], v[148:151], v[164:167], v[128:143]
	ds_read_b128 v[148:151], v218 offset:60448
	s_waitcnt lgkmcnt(3)
	v_mfma_f32_32x32x16_bf16 v[112:127], v[152:155], v[160:163], v[112:127]
	ds_read_b128 v[152:155], v218 offset:62976
	s_waitcnt lgkmcnt(3)
	v_mfma_f32_32x32x16_bf16 v[112:127], v[168:171], v[164:167], v[112:127]
	ds_read_b128 v[168:171], v218 offset:63008
	s_waitcnt lgkmcnt(3)
	v_mfma_f32_32x32x16_bf16 v[96:111], v[172:175], v[160:163], v[96:111]
	v_add_u32_e32 v0, 0x10000, v218
	ds_read_b128 v[172:175], v0
	s_waitcnt lgkmcnt(3)
	v_mfma_f32_32x32x16_bf16 v[96:111], v[148:151], v[164:167], v[96:111]
	v_add_u32_e32 v0, 0x10020, v218
	ds_read_b128 v[148:151], v0
	s_waitcnt lgkmcnt(3)
	v_mfma_f32_32x32x16_bf16 v[80:95], v[152:155], v[160:163], v[80:95]
	ds_read_b128 v[152:155], v226
	s_waitcnt lgkmcnt(3)
	v_mfma_f32_32x32x16_bf16 v[80:95], v[168:171], v[164:167], v[80:95]
	ds_read_b128 v[168:171], v227
	s_waitcnt lgkmcnt(3)
	v_mfma_f32_32x32x16_bf16 v[64:79], v[172:175], v[160:163], v[64:79]
	ds_read_b128 v[172:175], v228
	s_waitcnt lgkmcnt(3)
	v_mfma_f32_32x32x16_bf16 v[64:79], v[148:151], v[164:167], v[64:79]
	ds_read_b128 v[148:151], v229
	s_waitcnt lgkmcnt(3)
	v_mfma_f32_32x32x16_bf16 v[48:63], v[152:155], v[160:163], v[48:63]
	ds_read_b128 v[152:155], v230
	s_waitcnt lgkmcnt(3)
	v_mfma_f32_32x32x16_bf16 v[48:63], v[168:171], v[164:167], v[48:63]
	ds_read_b128 v[168:171], v231
	s_andn2_b64 vcc, exec, s[94:95]
	s_cbranch_vccnz .Lattn_w1_none
	s_waitcnt vmcnt(3)
	ds_write_b128 v207, v[2:5]
	s_waitcnt vmcnt(2)
	ds_write_b128 v207, v[6:9] offset:8704
	s_waitcnt vmcnt(1)
	ds_write2_b64 v208, v[10:11], v[12:13] offset0:128 offset1:130
	s_waitcnt vmcnt(0)
	ds_write2_b64 v209, v[176:177], v[178:179] offset0:128 offset1:130
	s_waitcnt lgkmcnt(7)
	v_mfma_f32_32x32x16_bf16 v[32:47], v[172:175], v[160:163], v[32:47]
	s_waitcnt lgkmcnt(6)
	v_mfma_f32_32x32x16_bf16 v[32:47], v[148:151], v[164:167], v[32:47]
	s_waitcnt lgkmcnt(5)
	v_mfma_f32_32x32x16_bf16 v[16:31], v[152:155], v[160:163], v[16:31]
	s_waitcnt lgkmcnt(4)
	v_mfma_f32_32x32x16_bf16 v[16:31], v[168:171], v[164:167], v[16:31]
	v_add_f32_e32 v235, v235, v224
	s_branch .LBB0_312
.Lattn_w1_none:
	s_waitcnt lgkmcnt(3)
	v_mfma_f32_32x32x16_bf16 v[32:47], v[172:175], v[160:163], v[32:47]
	s_waitcnt lgkmcnt(2)
	v_mfma_f32_32x32x16_bf16 v[32:47], v[148:151], v[164:167], v[32:47]
	s_waitcnt lgkmcnt(1)
	v_mfma_f32_32x32x16_bf16 v[16:31], v[152:155], v[160:163], v[16:31]
	s_waitcnt lgkmcnt(0)
	v_mfma_f32_32x32x16_bf16 v[16:31], v[168:171], v[164:167], v[16:31]
	v_add_f32_e32 v235, v235, v224
	s_branch .LBB0_312
